# v15 + w_in skinny GEMM (forget logits, meta K/V) moved behind the P4 GEMM units
# speedup vs baseline: 1.0002x; 1.0002x over previous
.LBB0_654:
	s_or_b64 exec, exec, s[2:3]
	s_barrier
.LBB0_666:
	s_mov_b64 s[2:3], s[90:91]
	v_mbcnt_lo_u32_b32 v1, -1, 0
	v_mbcnt_hi_u32_b32 v1, -1, v1
	s_cmpk_gt_i32 s22, 0xbff
	s_waitcnt vmcnt(30)
	v_add_u32_e32 v2, s74, v1
	s_nop 0
	v_readfirstlane_b32 s12, v2
	s_cbranch_scc1 .LBB0_686
	s_load_dwordx2 s[4:5], s[2:3], 0xc8
	s_movk_i32 s0, 0x181
	v_and_b32_e32 v0, 63, v1
	v_lshlrev_b32_e32 v0, 4, v0
	s_waitcnt lgkmcnt(0)
	s_add_u32 s2, s4, 0x620000
	s_addc_u32 s3, s5, 0
	s_ashr_i32 s23, s22, 31
	s_lshr_b32 s1, s23, 29
	s_add_i32 s1, s22, s1
	s_ashr_i32 s6, s1, 3
	s_and_b32 s1, s1, -8
	s_sub_i32 s1, s22, s1
	s_cmp_lt_i32 s1, 0
	s_cselect_b32 s0, s0, 0x180
	s_mul_i32 s0, s1, s0
	s_add_i32 s0, s0, s6
	s_mul_hi_i32 s1, s0, 0x2aaaaaab
	s_lshr_b32 s6, s1, 31
	s_ashr_i32 s1, s1, 6
	s_add_i32 s1, s1, s6
	s_lshl_b32 s6, s1, 3
	s_mulk_i32 s1, 0x180
	s_sub_i32 s0, s0, s1
	s_sext_i32_i16 s1, s0
	s_bfe_u32 s1, s1, 0x3001c
	s_add_i32 s1, s0, s1
	s_sext_i32_i16 s7, s1
	s_and_b32 s1, s1, 0xfff8
	s_sub_i32 s0, s0, s1
	s_sext_i32_i16 s0, s0
	s_lshr_b32 s8, s7, 3
	s_add_i32 s30, s6, s0
	s_cmp_lt_u32 s12, 64
	s_cselect_b64 s[6:7], -1, 0
	s_ashr_i32 s31, s30, 31
	s_cmp_gt_u32 s12, 63
	s_cbranch_scc1 .LBB0_669
	s_lshl_b64 s[0:1], s[30:31], 10
	s_add_u32 s0, s2, s0
	s_addc_u32 s1, s3, s1
	s_add_i32 m0, 0, 0x20000
	s_nop 0
	global_load_lds_dwordx4 v0, s[0:1]

.LBB0_714:
	s_mov_b64 s[2:3], s[90:91]
	s_cmpk_gt_i32 s22, 0x600
	v_mbcnt_lo_u32_b32 v0, -1, 0
	v_mbcnt_hi_u32_b32 v0, -1, v0
	s_cbranch_scc1 .Lsk4_done
	s_load_dwordx2 s[0:1], s[2:3], 0xc8
	s_waitcnt vmcnt(18)
	v_and_b32_e32 v42, 15, v0
	v_and_b32_e32 v1, -16, v0
	v_lshl_add_u32 v43, v0, 4, 0
	v_ashrrev_i32_e32 v0, 2, v0
	s_waitcnt lgkmcnt(0)
	s_add_u32 s23, s0, 0x11400000
	s_addc_u32 s25, s1, 0
	s_add_u32 s26, s0, 0x1f600000
	s_addc_u32 s27, s1, 0
	s_add_u32 s6, s0, 0x620000
	v_lshlrev_b32_e32 v2, 13, v42
	s_addc_u32 s7, s1, 0
	s_lshl_b32 s8, s81, 10
	v_and_b32_e32 v0, -4, v0
	v_add3_u32 v4, v1, s8, v2
	s_cmp_eq_u32 s81, 0
	v_ashrrev_i32_e32 v1, 31, v0
	v_mov_b32_e32 v5, 0
	s_cselect_b64 s[2:3], -1, 0
	s_waitcnt vmcnt(8)
	v_mul_u32_u24_e32 v38, 0x3000, v42
	v_lshl_add_u64 v[2:3], v[0:1], 2, s[0:1]
	s_mov_b64 s[4:5], 0x300000
	s_add_u32 s10, s0, 0x27600000
	v_lshl_add_u64 v[36:37], v[2:3], 0, s[4:5]
	s_addc_u32 s11, s1, 0
	v_lshlrev_b32_e32 v2, 1, v38
	v_mov_b32_e32 v3, v5
	s_add_u32 s12, s0, 0x1b400000
	v_lshl_add_u64 v[2:3], s[0:1], 0, v[2:3]
	s_addc_u32 s13, s1, 0
	v_lshl_add_u64 v[0:1], v[0:1], 1, v[2:3]
	s_mov_b64 s[0:1], 0x47a02000
	v_lshl_add_u64 v[38:39], v[0:1], 0, s[0:1]
	v_cndmask_b32_e64 v0, 0, 1, s[2:3]
	s_mov_b32 s9, 0
	s_waitcnt vmcnt(7)
	v_or_b32_e32 v44, 0x4000, v42
	v_add_u32_e32 v6, 64, v4
	v_mov_b32_e32 v7, v5
	v_add_u32_e32 v8, 0x80, v4
	v_mov_b32_e32 v9, v5
	v_add_u32_e32 v10, 0xc0, v4
	v_mov_b32_e32 v11, v5
	v_add_u32_e32 v12, 0x100, v4
	v_mov_b32_e32 v13, v5
	v_add_u32_e32 v14, 0x140, v4
	v_mov_b32_e32 v15, v5
	v_add_u32_e32 v16, 0x180, v4
	v_mov_b32_e32 v17, v5
	v_add_u32_e32 v18, 0x1c0, v4
	v_mov_b32_e32 v19, v5
	v_add_u32_e32 v20, 0x200, v4
	v_mov_b32_e32 v21, v5
	v_add_u32_e32 v22, 0x240, v4
	v_mov_b32_e32 v23, v5
	v_add_u32_e32 v24, 0x280, v4
	v_mov_b32_e32 v25, v5
	v_add_u32_e32 v26, 0x2c0, v4
	v_mov_b32_e32 v27, v5
	v_add_u32_e32 v28, 0x300, v4
	v_mov_b32_e32 v29, v5
	v_add_u32_e32 v30, 0x340, v4
	v_mov_b32_e32 v31, v5
	v_add_u32_e32 v32, 0x380, v4
	v_mov_b32_e32 v33, v5
	v_add_u32_e32 v34, 0x3c0, v4
	v_mov_b32_e32 v35, v5
	s_lshl_b32 s14, s22, 4
	s_lshl_b32 s30, s72, 4
	v_add_u32_e32 v45, s8, v43
	s_movk_i32 s31, 0x7fff
	s_mov_b32 s34, 0xffff0000
	v_cmp_ne_u32_e64 s[2:3], 1, v0
	s_mov_b32 s35, s22
	s_branch .LBB0_657

.LBB0_664:
	s_andn2_b64 vcc, exec, s[4:5]
	s_cbranch_vccnz .LBB0_656
	v_ashrrev_i32_e32 v41, 31, v40
	v_lshlrev_b64 v[40:41], 6, v[40:41]
	v_lshl_add_u64 v[40:41], v[36:37], 0, v[40:41]
	global_store_dwordx4 v[40:41], v[0:3], off
	s_branch .LBB0_656
.Lsk4_done:
	s_mov_b64 s[4:5], s[90:91]
	v_mbcnt_lo_u32_b32 v0, -1, 0
	v_mbcnt_hi_u32_b32 v0, -1, v0
	s_getreg_b32 s6, hwreg(HW_REG_XCC_ID, 0, 4)
	s_waitcnt vmcnt(0)
	v_sub_u32_e32 v0, 0, v0
	v_cmp_eq_u32_e32 vcc, s74, v0
	s_waitcnt vmcnt(0) lgkmcnt(0)
	s_barrier
	s_and_saveexec_b64 s[2:3], vcc
	s_cbranch_execz .LBB0_781
	s_add_i32 s0, 0, 0x22160
	v_mov_b32_e32 v0, s0
	s_load_dwordx2 s[4:5], s[4:5], 0xc8
	s_waitcnt vmcnt(0) expcnt(0) lgkmcnt(0)
	ds_read_b32 v2, v0
	s_add_i32 s0, 0, 0x22164
	v_mov_b32_e32 v0, s0
	ds_read_b32 v1, v0
	s_and_b32 s23, s6, 15
	s_waitcnt lgkmcnt(1)
	v_cmp_ne_u32_e32 vcc, 0, v2
	s_cbranch_vccnz .LBB0_730
	v_readlane_b32 s6, v255, 0
	v_readlane_b32 s7, v255, 1
	s_load_dwordx2 s[0:1], s[6:7], 0x4
	s_add_u32 s6, s4, 0x4200
	s_addc_u32 s7, s5, 0
	s_add_u32 s8, s4, 0x4400
	s_addc_u32 s9, s5, 0
	s_add_u32 s10, s4, 0x4500
	s_addc_u32 s11, s5, 0
	s_add_u32 s12, s4, 0x4600
	s_addc_u32 s13, s5, 0
	s_add_u32 s14, s4, 0x4700
	s_addc_u32 s15, s5, 0
	s_add_u32 s16, s4, 0x4800
	s_addc_u32 s17, s5, 0
	s_add_u32 s18, s4, 0x4900
	s_addc_u32 s19, s5, 0
	s_add_u32 s20, s4, 0x4a00
	s_addc_u32 s21, s5, 0
	s_add_u32 s30, s4, 0x4b00
	s_addc_u32 s31, s5, 0
	s_add_u32 s34, s4, 0x4c00
	s_addc_u32 s35, s5, 0
	s_add_u32 s36, s4, 0x4d00
	s_addc_u32 s37, s5, 0
	s_add_u32 s38, s4, 0x4e00
	s_addc_u32 s39, s5, 0
	s_add_u32 s40, s4, 0x4f00
	s_addc_u32 s41, s5, 0
	s_add_u32 s42, s4, 0x5000
	s_addc_u32 s43, s5, 0
	s_add_u32 s44, s4, 0x5100
	s_addc_u32 s45, s5, 0
	s_add_u32 s46, s4, 0x5200
	s_addc_u32 s47, s5, 0
	s_waitcnt lgkmcnt(0)
	s_mul_i32 s25, s0, s72
	s_add_u32 s48, s4, 0x5300
	s_mul_i32 s25, s25, s1
	s_addc_u32 s49, s5, 0
	s_mov_b32 s26, 1
	v_mov_b32_e32 v16, 0
	s_branch .LBB0_718
